# in-projection schedule rebalanced: the 4 workgroups per XCD that also own a K or V^T unit (25 units) take the cheapest-epilogue (kind-0) units of each 32-unit window, the other 28 share the rest; ever
# speedup vs baseline: 1.0121x; 1.0095x over previous
;     __device__ __forceinline__ bool next(int i, Unit& u) const {
;         if (G == 256) {
;             if (i < 24) { const int l = i * 32 + (c >> 3); int pm = l / 6, pn = 6 * (c & 7) + l % 6; pn = (pn % 3) * 16 + pn / 3;
;                 u.pm = pm; u.pn = pn; u.kind = pn >> 4; u.A = U + (size_t)pm * TILE; u.B = Win + (size_t)pn * TILE; return true; }
;             if (i > 24 || c >= 32) return false;
;             int L = c;
;             if (L < 16) { u.pm = L >> 2; u.pn = L & 3; u.kind = 3; u.A = Memn + (size_t)u.pm * TILE; u.B = Wkv + (size_t)u.pn * TILE; }
;             else { L -= 16; u.pm = L >> 2; u.pn = L & 3; u.kind = 4; u.A = Wkv + (size_t)(4 + u.pm) * TILE; u.B = Memn + (size_t)u.pn * TILE; }
;             return true;
.LBB0_131:
	s_andn2_b64 vcc, exec, s[30:31]
	s_cbranch_vccnz .LBB0_133
	v_readlane_b32 s28, v255, 26
	s_lshl_b32 s12, s54, 5
	s_mul_i32 s29, s12, 0xaaab
	s_lshr_b32 s29, s29, 17
	s_mul_i32 s29, s29, 3
	s_sub_i32 s29, s12, s29
	s_cmp_eq_u32 s29, 0
	s_cbranch_scc1 .Lsch_o0
	s_sub_i32 s29, 3, s29
.Lsch_o0:
	s_cmp_lt_u32 s28, 4
	s_cbranch_scc0 .Lsch_reg
	s_mul_i32 s28, s28, 3
	s_add_i32 s12, s12, s29
	s_add_i32 s12, s12, s28
	s_branch .Lsch_done
.Lsch_reg:
	s_sub_i32 s28, s28, 4
	s_cmp_lt_u32 s28, s29
	s_cbranch_scc1 .Lsch_same
	s_sub_i32 s28, s28, s29
	s_cmp_lt_u32 s28, 8
	s_cbranch_scc0 .Lsch_tail
	s_add_i32 s12, s12, s29
	s_add_i32 s12, s12, 1
	s_lshr_b32 s29, s28, 1
	s_mul_i32 s29, s29, 3
	s_add_i32 s12, s12, s29
	s_and_b32 s28, s28, 1
	s_add_i32 s12, s12, s28
	s_branch .Lsch_done
.Lsch_tail:
	s_add_i32 s28, s28, s29
	s_add_i32 s28, s28, 4
.Lsch_same:
	s_add_i32 s12, s12, s28
.Lsch_done:
	s_mul_hi_i32 s28, s12, 0x2aaaaaab
	s_lshr_b32 s29, s28, 31
	s_add_i32 s80, s28, s29
	s_mul_i32 s28, s80, 6
	s_sub_i32 s12, s12, s28
	v_readlane_b32 s28, v255, 31
	s_add_i32 s12, s12, s28
	s_mul_i32 s28, s12, 0x56
	s_bfe_u32 s29, s28, 0x1000f
	s_bfe_u32 s28, s28, 0x80008
	s_add_i32 s28, s28, s29
	s_mul_i32 s29, s28, 3
	s_sub_i32 s12, s12, s29
	s_sext_i32_i8 s12, s12
	s_lshl_b32 s12, s12, 4
	s_sext_i32_i8 s28, s28
	s_add_i32 s34, s12, s28
	s_ashr_i32 s81, s80, 31
	s_ashr_i32 s12, s34, 4
	s_lshl_b64 s[28:29], s[80:81], 19
	s_add_u32 s28, s24, s28
	s_addc_u32 s29, s25, s29
	s_ashr_i32 s35, s34, 31
	s_lshl_b64 s[30:31], s[34:35], 19
	s_add_u32 s40, s26, s30
	s_addc_u32 s41, s27, s31
	s_mov_b64 s[94:95], -1
